# slot-parity merge roles plus one static s_setprio 1 for the slot-1 workgroup of each CU
# baseline (speedup 1.0000x reference)
.LBB0_117:
	s_or_b64 exec, exec, s[52:53]
	s_add_u32 s12, s94, 0x20c0000
	s_addc_u32 s13, s95, 0
	s_add_u32 s0, s94, 0x48e8000
	s_addc_u32 s1, s95, 0
	s_getreg_b32 s14, hwreg(HW_REG_HW_ID, 16, 4)
	s_and_b32 s14, s14, 1
	s_cmp_eq_u32 s14, 0
	s_cbranch_scc1 .Lprio_skip
	s_setprio 1
.Lprio_skip:
	v_writelane_b32 v238, s0, 38
	s_cmpk_lt_i32 s64, 0xa00
	s_mov_b32 s97, 0
	v_writelane_b32 v238, s1, 39
	s_cselect_b64 s[0:1], -1, 0
	v_writelane_b32 v238, s0, 40
	s_mov_b32 s3, s97
	v_lshl_add_u64 v[0:1], v[0:1], 2, s[50:51]
	v_writelane_b32 v238, s1, 41
	s_add_u32 s0, s94, 0x130e8000
	s_addc_u32 s1, s95, 0
	v_writelane_b32 v238, s0, 42
	s_waitcnt lgkmcnt(0)
	s_barrier
	v_writelane_b32 v238, s1, 43
	s_add_u32 s0, s94, 0x120e8000
	s_addc_u32 s1, s95, 0
	v_writelane_b32 v238, s0, 44
	v_mov_b32_e32 v216, 0x168e8000
	s_nop 0
	v_writelane_b32 v238, s1, 45
	s_add_u32 s0, s94, 0x110e8000
	s_addc_u32 s1, s95, 0
	s_add_u32 s74, s94, 0xf8e8000
	v_writelane_b32 v238, s0, 46
	s_addc_u32 s75, s95, 0
	v_mov_b32_e32 v217, 0x138e8000
	v_writelane_b32 v238, s1, 47
	s_add_u32 s0, s94, 0xe0e8000
	s_addc_u32 s1, s95, 0
	v_writelane_b32 v238, s0, 48
	v_mov_b32_e32 v165, 0
	v_mov_b32_e32 v218, 1
	v_writelane_b32 v238, s1, 49
	s_add_u32 s0, s94, 0xc8e8000
	s_addc_u32 s1, s95, 0
	v_writelane_b32 v238, s0, 50
	s_cmpk_lt_i32 s64, 0x80
	v_mov_b32_e32 v219, 0x3ecc95a3
	v_writelane_b32 v238, s1, 51
	s_cselect_b64 s[0:1], -1, 0
	v_writelane_b32 v238, s0, 52
	s_add_u32 s15, s94, 0x1e80000
	v_mov_b32_e32 v220, 1.0
	v_writelane_b32 v238, s1, 53
	s_addc_u32 s0, s95, 0
	s_add_u32 s90, s94, 0x24c0000
	s_addc_u32 s91, s95, 0
	v_writelane_b32 v238, s0, 54
	s_add_u32 s0, s94, 0x88e8000
	s_addc_u32 s1, s95, 0
	v_writelane_b32 v238, s0, 55
	s_cmpk_lt_i32 s64, 0x200
	v_mov_b32_e32 v166, 0x12000
	v_writelane_b32 v238, s1, 56
	s_cselect_b64 s[0:1], -1, 0
	s_add_u32 s6, s94, 0x1b148000
	s_addc_u32 s7, s95, 0
	s_add_u32 s85, s94, 0x1b948000
	s_addc_u32 s33, s95, 0
	s_add_u32 s28, s94, 0x1c948000
	v_writelane_b32 v238, s0, 57
	s_addc_u32 s29, s95, 0
	s_lshl_b64 s[34:35], s[2:3], 11
	v_writelane_b32 v238, s1, 58
	s_add_u32 s0, s94, 0x1a00000
	s_addc_u32 s1, s95, 0
	v_writelane_b32 v238, s0, 59
	v_mov_b32_e32 v168, 0x12004
	v_mov_b32_e32 v221, 0xf149f2ca
	v_writelane_b32 v238, s1, 60
	s_add_u32 s0, s94, 0x1800000
	s_addc_u32 s1, s95, 0
	v_writelane_b32 v238, s0, 61
	v_mov_b32_e32 v222, 0x41b17218
	v_mov_b32_e32 v223, 0x7f800000
	v_writelane_b32 v238, s1, 62
	s_add_u32 s0, s94, 0x1700000
	s_addc_u32 s1, s95, 0
	v_writelane_b32 v238, s0, 63
	v_mov_b32_e32 v224, 0x7fc00000
	v_readlane_b32 s48, v238, 20
	v_writelane_b32 v237, s1, 0
	s_add_u32 s0, s94, 0x1500000
	s_addc_u32 s1, s95, 0
	v_writelane_b32 v237, s0, 1
	v_readlane_b32 s54, v238, 26
	v_readlane_b32 s55, v238, 27
	v_writelane_b32 v237, s1, 2
	s_add_u32 s0, s94, 0x1400000
	s_addc_u32 s1, s95, 0
	v_writelane_b32 v237, s0, 3
	v_readlane_b32 s49, v238, 21
	v_readlane_b32 s50, v238, 22
	v_writelane_b32 v237, s1, 4
	s_add_u32 s0, s94, 0x48e1200
	s_addc_u32 s1, s95, 0
	s_add_u32 s8, s94, 0x48e1400
	s_addc_u32 s9, s95, 0
	s_add_u32 s20, s94, 0x48e1500
	s_addc_u32 s21, s95, 0
	s_add_u32 s16, s94, 0x48e1600
	v_writelane_b32 v237, s0, 5
	s_addc_u32 s17, s95, 0
	s_add_u32 s18, s94, 0x48e1700
	v_writelane_b32 v237, s1, 6
	s_mov_b64 s[0:1], 0x1400
	v_lshl_add_u64 v[162:163], v[0:1], 0, s[0:1]
	s_mov_b64 s[0:1], 0x2400
	s_addc_u32 s19, s95, 0
	v_lshl_add_u64 v[160:161], v[0:1], 0, s[0:1]
	s_add_u32 s0, s94, 0x48e1800
	s_addc_u32 s1, s95, 0
	v_writelane_b32 v237, s0, 7
	v_readlane_b32 s51, v238, 23
	v_mbcnt_lo_u32_b32 v0, -1, 0
	v_writelane_b32 v237, s1, 8
	s_add_u32 s0, s94, 0x48e1900
	s_addc_u32 s1, s95, 0
	v_writelane_b32 v237, s0, 9
	v_readlane_b32 s52, v238, 24
	v_readlane_b32 s53, v238, 25
	v_writelane_b32 v237, s1, 10
	s_add_u32 s0, s94, 0x48e1a00
	s_addc_u32 s1, s95, 0
	v_writelane_b32 v237, s0, 11
	v_readlane_b32 s56, v238, 28
	v_readlane_b32 s57, v238, 29
	v_writelane_b32 v237, s1, 12
	s_add_u32 s0, s94, 0x48e1b00
	s_addc_u32 s1, s95, 0
	v_writelane_b32 v237, s0, 13
	v_readlane_b32 s58, v238, 30
	v_readlane_b32 s59, v238, 31
	v_writelane_b32 v237, s1, 14
	s_add_u32 s0, s94, 0x48e1c00
	s_addc_u32 s1, s95, 0
	v_writelane_b32 v237, s0, 15
	v_readlane_b32 s60, v238, 32
	v_readlane_b32 s61, v238, 33
	v_writelane_b32 v237, s1, 16
	s_add_u32 s0, s94, 0x48e1d00
	s_addc_u32 s1, s95, 0
	v_writelane_b32 v237, s0, 17
	v_readlane_b32 s62, v238, 34
	v_readlane_b32 s63, v238, 35
	v_writelane_b32 v237, s1, 18
	s_add_u32 s0, s94, 0x48e1e00
	s_addc_u32 s1, s95, 0
	v_writelane_b32 v237, s0, 19
	v_mbcnt_hi_u32_b32 v215, -1, v0
	v_mov_b32_e32 v225, 0xff800000
	v_writelane_b32 v237, s1, 20
	s_add_u32 s0, s94, 0x48e1f00
	s_addc_u32 s1, s95, 0
	v_writelane_b32 v237, s0, 21
	s_mov_b32 s88, 0xfffffc0
	s_movk_i32 s89, 0x90
	v_writelane_b32 v237, s1, 22
	s_add_u32 s0, s94, 0x48e2000
	s_addc_u32 s1, s95, 0
	v_writelane_b32 v237, s0, 23
	s_movk_i32 s70, 0x210
	s_movk_i32 s71, 0x1800
	v_writelane_b32 v237, s1, 24
	s_add_u32 s0, s94, 0x48e2100
	s_addc_u32 s1, s95, 0
	v_writelane_b32 v237, s0, 25
	s_mov_b32 s26, 0x10000
	s_mov_b32 s27, 0x20000
	v_writelane_b32 v237, s1, 26
	s_add_u32 s0, s94, 0x48e2200
	s_addc_u32 s1, s95, 0
	v_writelane_b32 v237, s0, 27
	s_mov_b32 s84, 0x30000
	s_nop 0
	v_writelane_b32 v237, s1, 28
	s_add_u32 s0, s94, 0x48e2300
	s_addc_u32 s1, s95, 0
	v_writelane_b32 v237, s0, 29
	s_cmp_eq_u32 s30, 0
	s_nop 0
	v_writelane_b32 v237, s1, 30
	s_cselect_b64 s[0:1], -1, 0
	v_writelane_b32 v237, s0, 31
	s_cmp_eq_u32 s30, 1
	s_nop 0
	v_writelane_b32 v237, s1, 32
	s_cselect_b64 s[0:1], -1, 0
	v_writelane_b32 v237, s0, 33
	s_cmp_eq_u32 s30, 2
	s_nop 0
	v_writelane_b32 v237, s1, 34
	s_cselect_b64 s[0:1], -1, 0
	v_writelane_b32 v237, s0, 35
	s_cmp_eq_u32 s30, 3
	s_nop 0
	v_writelane_b32 v237, s1, 36
	s_cselect_b64 s[0:1], -1, 0
	v_writelane_b32 v237, s0, 37
	s_cmp_eq_u32 s30, 4
	s_nop 0
	v_writelane_b32 v237, s1, 38
	s_cselect_b64 s[0:1], -1, 0
	v_writelane_b32 v237, s0, 39
	s_cmp_eq_u32 s30, 5
	s_nop 0
	v_writelane_b32 v237, s1, 40
	s_cselect_b64 s[0:1], -1, 0
	v_writelane_b32 v237, s0, 41
	s_cmp_eq_u32 s30, 6
	s_nop 0
	v_writelane_b32 v237, s1, 42
	s_cselect_b64 s[0:1], -1, 0
	v_writelane_b32 v237, s0, 43
	s_cmp_eq_u32 s30, 7
	s_nop 0
	v_writelane_b32 v237, s1, 44
	s_cselect_b64 s[0:1], -1, 0
	v_writelane_b32 v237, s0, 45
	s_cmp_eq_u32 s30, 8
	s_nop 0
	v_writelane_b32 v237, s1, 46
	s_cselect_b64 s[0:1], -1, 0
	v_writelane_b32 v237, s0, 47
	s_cmp_eq_u32 s30, 9
	s_nop 0
	v_writelane_b32 v237, s1, 48
	s_cselect_b64 s[0:1], -1, 0
	v_writelane_b32 v237, s0, 49
	s_cmp_eq_u32 s30, 10
	s_nop 0
	v_writelane_b32 v237, s1, 50
	s_cselect_b64 s[0:1], -1, 0
	v_writelane_b32 v237, s0, 51
	s_cmp_eq_u32 s30, 11
	s_nop 0
	v_writelane_b32 v237, s1, 52
	s_cselect_b64 s[0:1], -1, 0
	v_writelane_b32 v237, s0, 53
	s_cmp_eq_u32 s30, 12
	s_nop 0
	v_writelane_b32 v237, s1, 54
	s_cselect_b64 s[0:1], -1, 0
	v_writelane_b32 v237, s0, 55
	s_cmp_eq_u32 s30, 13
	s_nop 0
	v_writelane_b32 v237, s1, 56
	s_cselect_b64 s[0:1], -1, 0
	v_writelane_b32 v237, s0, 57
	s_cmp_eq_u32 s30, 14
	s_nop 0
	v_writelane_b32 v237, s1, 58
	s_cselect_b64 s[0:1], -1, 0
	v_writelane_b32 v237, s0, 59
	s_cmp_eq_u32 s30, 15
	s_nop 0
	v_writelane_b32 v237, s1, 60
	s_cselect_b64 s[0:1], -1, 0
	v_writelane_b32 v237, s0, 61
	s_nop 1
	v_writelane_b32 v237, s1, 62
	s_add_u32 s0, s94, 0x48e4400
	s_addc_u32 s1, s95, 0
	v_writelane_b32 v237, s0, 63
	s_nop 1
	v_writelane_b32 v236, s1, 0
	s_add_u32 s0, s94, 0x48e4500
	s_addc_u32 s1, s95, 0
	v_writelane_b32 v236, s0, 1
	s_cmpk_lt_i32 s64, 0x600
	s_nop 0
	v_writelane_b32 v236, s1, 2
	s_cselect_b64 s[0:1], -1, 0
	s_add_u32 s46, s94, 0x198e8000
	v_writelane_b32 v236, s0, 3
	s_addc_u32 s47, s95, 0
	s_nop 0
	v_writelane_b32 v236, s1, 4
	s_add_u32 s0, s94, 0x1b0e8000
	s_addc_u32 s1, s95, 0
	v_writelane_b32 v236, s0, 5
	s_nop 1
	v_writelane_b32 v236, s1, 6
	s_add_u32 s0, s94, 0x1d148000
	v_writelane_b32 v236, s0, 7
	s_addc_u32 s0, s95, 0
	v_writelane_b32 v236, s0, 8
	s_add_u32 s0, s94, 0x1e148000
	v_writelane_b32 v236, s0, 9
	s_addc_u32 s0, s95, 0
	v_writelane_b32 v236, s0, 10
	s_add_u32 s0, s94, 0x2080000
	v_writelane_b32 v236, s0, 11
	s_addc_u32 s0, s95, 0
	v_writelane_b32 v236, s0, 12
	s_add_u32 s0, s94, 0x20a0000
	v_writelane_b32 v236, s0, 13
	s_addc_u32 s0, s95, 0
	v_writelane_b32 v236, s0, 14
	s_add_u32 s0, s94, 0x1f148000
	s_addc_u32 s1, s95, 0
	v_writelane_b32 v236, s0, 15
	s_nop 1
	v_writelane_b32 v236, s1, 16
	s_add_u32 s0, s94, 0x1f1c8000
	v_writelane_b32 v236, s0, 17
	s_addc_u32 s0, s95, 0
	v_writelane_b32 v236, s0, 18
	s_lshl_b32 s0, s64, 8
	v_writelane_b32 v236, s0, 19
	s_lshl_b32 s0, s2, 8
	v_writelane_b32 v236, s0, 20
	s_lshl_b64 s[0:1], s[64:65], 8
	v_writelane_b32 v236, s0, 21
	s_nop 1
	v_writelane_b32 v236, s1, 22
	s_lshl_b64 s[0:1], s[2:3], 8
	v_writelane_b32 v236, s0, 23
	s_nop 1
	v_writelane_b32 v236, s1, 24
	s_lshl_b64 s[0:1], s[64:65], 13
	s_add_u32 s4, s72, s0
	s_addc_u32 s5, s73, s1
	s_add_u32 s4, s4, 0x2000000
	s_addc_u32 s5, s5, 0
	v_writelane_b32 v236, s4, 25
	s_lshl_b64 s[76:77], s[2:3], 13
	s_nop 0
	v_writelane_b32 v236, s5, 26
	s_lshl_b64 s[4:5], s[64:65], 12
	s_add_u32 s24, s94, s4
	s_addc_u32 s25, s95, s5
	s_add_u32 s4, s24, 0x58e8000
	s_addc_u32 s5, s25, 0
	v_writelane_b32 v236, s4, 27
	s_nop 1
	v_writelane_b32 v236, s5, 28
	s_lshl_b64 s[4:5], s[2:3], 12
	s_add_u32 s0, s54, s0
	s_addc_u32 s1, s55, s1
	s_add_u32 s0, s0, 16
	s_addc_u32 s1, s1, 0
	v_writelane_b32 v236, s0, 29
	s_nop 1
	v_writelane_b32 v236, s1, 30
	s_add_u32 s0, s24, 0x1e00000
	s_addc_u32 s1, s25, 0
	v_writelane_b32 v236, s0, 31
	s_lshl_b32 s3, s2, 1
	s_lshl_b32 s24, s2, 6
	v_writelane_b32 v236, s1, 32
	s_lshl_b32 s0, s64, 1
	v_writelane_b32 v236, s0, 33
	s_lshl_b32 s0, s64, 2
	v_writelane_b32 v236, s0, 34
	s_lshl_b32 s0, s64, 6
	v_writelane_b32 v236, s0, 35
	s_mov_b32 s0, s64
	v_writelane_b32 v236, s0, 36
	s_movk_i32 s25, 0x48
	s_nop 0
	v_writelane_b32 v236, s1, 37
	s_lshl_b32 s0, s64, 11
	v_writelane_b32 v236, s0, 38
	s_lshl_b32 s0, s2, 11
	v_writelane_b32 v236, s0, 39
	s_mov_b32 s1, 0
	s_lshl_b32 s0, s2, 2
	v_writelane_b32 v236, s0, 40
	s_nop 1
	v_writelane_b32 v236, s1, 41
	v_writelane_b32 v236, s8, 42
	s_nop 1
	v_writelane_b32 v236, s9, 43
	v_writelane_b32 v236, s20, 44
	s_nop 1
	v_writelane_b32 v236, s21, 45
	v_writelane_b32 v236, s16, 46
	s_nop 1
	v_writelane_b32 v236, s17, 47
	v_writelane_b32 v236, s18, 48
	s_nop 1
	v_writelane_b32 v236, s19, 49
	v_writelane_b32 v236, s14, 50
	v_writelane_b32 v236, s74, 51
	s_nop 1
	v_writelane_b32 v236, s75, 52
	v_writelane_b32 v236, s46, 53
	s_nop 1
	v_writelane_b32 v236, s47, 54
	s_branch .LBB0_121
